# v_rm_m1 + M1 first-tile row statistics loaded before the tile loop (overlaps the K-loop fill)
# baseline (speedup 1.0000x reference)
.LBB0_934:
	s_waitcnt lgkmcnt(0)
	s_add_u32 s4, s8, s81
	s_addc_u32 s5, s9, 0
	s_add_u32 s4, s4, 0x9600000
	s_addc_u32 s5, s5, 0
	s_add_u32 s6, s6, s84
	s_addc_u32 s7, s7, 0
	s_add_u32 s6, s6, 0x100000
	v_bfe_u32 v12, v2, 4, 2
	s_addc_u32 s7, s7, 0
	v_readlane_b32 s30, v253, 50
	v_and_b32_e32 v146, 15, v0
	v_lshl_or_b32 v146, s12, 6, v146
	v_bfe_u32 v210, v0, 4, 2
	v_lshlrev_b32_e32 v210, 16, v210
	v_or_b32_e32 v212, 0x4000, v210
	v_or_b32_e32 v214, 0x8000, v210
	v_or_b32_e32 v216, 0xc000, v210
	v_lshl_add_u32 v146, s30, 8, v146
	v_ashrrev_i32_e32 v147, 31, v146
	v_lshl_add_u64 v[136:137], v[146:147], 2, s[6:7]
	v_mov_b32_e32 v213, v4
	v_lshl_add_u64 v[138:139], v[136:137], 0, v[212:213]
	v_mov_b32_e32 v215, v4
	v_mov_b32_e32 v211, v4
	global_load_dword v145, v[138:139], off
	v_lshl_add_u64 v[138:139], v[136:137], 0, v[214:215]
	v_mov_b32_e32 v217, v4
	v_lshl_add_u64 v[134:135], v[136:137], 0, v[210:211]
	global_load_dword v148, v[138:139], off
	v_lshl_add_u64 v[138:139], v[136:137], 0, v[216:217]
	global_load_dword v144, v[134:135], off
	global_load_dword v150, v[134:135], off offset:64
	global_load_dword v154, v[134:135], off offset:128
	global_load_dword v159, v[134:135], off offset:192
	global_load_dword v163, v[134:135], off offset:512
	global_load_dword v167, v[134:135], off offset:576
	global_load_dword v171, v[134:135], off offset:640
	global_load_dword v149, v[138:139], off
	v_lshl_add_u64 v[138:139], v[136:137], 0, 64
	v_lshl_add_u64 v[140:141], v[138:139], 0, v[212:213]
	global_load_dword v151, v[140:141], off
	v_lshl_add_u64 v[140:141], v[138:139], 0, v[214:215]
	v_lshl_add_u64 v[138:139], v[138:139], 0, v[216:217]
	global_load_dword v152, v[140:141], off
	global_load_dword v153, v[138:139], off
	v_lshl_add_u64 v[138:139], v[136:137], 0, s[68:69]
	v_lshl_add_u64 v[140:141], v[138:139], 0, v[212:213]
	global_load_dword v155, v[140:141], off
	v_lshl_add_u64 v[140:141], v[138:139], 0, v[214:215]
	v_lshl_add_u64 v[138:139], v[138:139], 0, v[216:217]
	global_load_dword v157, v[140:141], off
	global_load_dword v158, v[138:139], off
	s_mov_b64 s[34:35], 0xc0
	v_lshl_add_u64 v[138:139], v[136:137], 0, s[34:35]
	v_lshl_add_u64 v[140:141], v[138:139], 0, v[212:213]
	global_load_dword v160, v[140:141], off
	v_lshl_add_u64 v[140:141], v[138:139], 0, v[214:215]
	v_lshl_add_u64 v[138:139], v[138:139], 0, v[216:217]
	global_load_dword v161, v[140:141], off
	global_load_dword v162, v[138:139], off
	s_mov_b64 s[34:35], 0x200
	v_lshl_add_u64 v[138:139], v[136:137], 0, s[34:35]
	v_lshl_add_u64 v[140:141], v[138:139], 0, v[212:213]
	global_load_dword v164, v[140:141], off
	v_lshl_add_u64 v[140:141], v[138:139], 0, v[214:215]
	v_lshl_add_u64 v[138:139], v[138:139], 0, v[216:217]
	global_load_dword v165, v[140:141], off
	global_load_dword v166, v[138:139], off
	s_mov_b64 s[34:35], 0x240
	v_lshl_add_u64 v[138:139], v[136:137], 0, s[34:35]
	v_lshl_add_u64 v[140:141], v[138:139], 0, v[212:213]
	global_load_dword v168, v[140:141], off
	v_lshl_add_u64 v[140:141], v[138:139], 0, v[214:215]
	v_lshl_add_u64 v[138:139], v[138:139], 0, v[216:217]
	global_load_dword v169, v[140:141], off
	global_load_dword v170, v[138:139], off
	s_mov_b64 s[34:35], 0x280
	v_lshl_add_u64 v[138:139], v[136:137], 0, s[34:35]
	v_lshl_add_u64 v[140:141], v[138:139], 0, v[212:213]
	global_load_dword v172, v[140:141], off
	v_lshl_add_u64 v[140:141], v[138:139], 0, v[214:215]
	v_lshl_add_u64 v[138:139], v[138:139], 0, v[216:217]
	global_load_dword v141, v[140:141], off
	s_mov_b64 s[34:35], 0x2c0
	global_load_dword v138, v[138:139], off
	v_lshl_add_u64 v[136:137], v[136:137], 0, s[34:35]
	global_load_dword v139, v[134:135], off offset:704
	v_lshl_add_u64 v[134:135], v[136:137], 0, v[212:213]
	global_load_dword v173, v[134:135], off
	v_lshl_add_u64 v[134:135], v[136:137], 0, v[214:215]
	global_load_dword v174, v[134:135], off
	v_lshl_add_u64 v[134:135], v[136:137], 0, v[216:217]
	global_load_dword v136, v[134:135], off
	v_add_u32_e32 v142, 0x80, v146
	v_ashrrev_i32_e32 v143, 31, v142
	s_and_b32 s13, s13, 3
	v_lshlrev_b32_e32 v13, 3, v12
	s_ashr_i32 s8, s11, 31
	v_lshl_or_b32 v226, s13, 6, v13
	v_lshlrev_b32_e32 v13, 14, v9
	s_lshr_b32 s8, s8, 26
	v_and_b32_e32 v13, 0xffff8000, v13
	v_and_b32_e32 v11, 15, v2
	s_add_i32 s8, s11, s8
	v_lshlrev_b32_e32 v14, 4, v12
	v_lshlrev_b32_e32 v2, 2, v2
	v_lshl_add_u32 v8, v8, 11, v13
	v_and_b32_e32 v9, 1, v9
	s_ashr_i32 s55, s8, 6
	v_lshl_or_b32 v5, s12, 6, v11
	v_lshl_or_b32 v11, v11, 6, v14
	s_lshl_b32 s8, s12, 13
	v_and_b32_e32 v2, 32, v2
	v_lshl_or_b32 v8, v9, 6, v8
	v_bitop3_b32 v15, v11, s8, v2 bitop3:0xde
	s_lshl_b32 s8, s13, 12
	v_lshl_add_u32 v206, v10, 1, v8
	v_lshlrev_b32_e32 v8, 14, v3
	s_cmp_gt_i32 s11, 63
	v_and_b32_e32 v8, 0xffff8000, v8
	v_readlane_b32 s12, v253, 54
	v_bitop3_b32 v11, v11, s8, v2 bitop3:0xde
	s_waitcnt vmcnt(8)
	s_barrier
	s_waitcnt vmcnt(6)
	s_cselect_b64 s[8:9], -1, 0
	s_add_i32 s56, s55, -2
	v_lshlrev_b32_e32 v2, 14, v12
	v_lshl_add_u32 v6, v6, 11, v8
	v_and_b32_e32 v3, 1, v3
	v_readlane_b32 s13, v253, 55
	s_cmpk_lt_u32 s10, 0x100
	v_or_b32_e32 v12, 0x1000, v2
	v_or_b32_e32 v14, 0x2000, v2
	v_or_b32_e32 v16, 0x3000, v2
	v_lshl_or_b32 v3, v3, 6, v6
	v_mov_b32_e32 v229, 0
	s_mov_b32 s59, s12
	v_readlane_b32 s12, v253, 50
	s_cselect_b64 s[10:11], -1, 0
	v_mov_b32_e32 v207, v4
	v_lshl_add_u32 v208, v7, 1, v3
	v_mov_b32_e32 v209, v4
	s_mov_b32 s57, 0
	s_mov_b32 s60, -1
	v_lshlrev_b32_e32 v210, 2, v2
	v_lshlrev_b32_e32 v212, 2, v12
	v_lshlrev_b32_e32 v214, 2, v14
	v_lshlrev_b32_e32 v216, 2, v16
	v_add_u32_e32 v227, 0, v11
	v_add_u32_e32 v228, 0, v15
	v_mov_b32_e32 v230, 0
	v_mov_b32_e32 v231, 0
	v_mov_b32_e32 v232, 0
	s_mov_b32 s58, s12
	v_mov_b32_e32 v2, 0
	v_mov_b32_e32 v3, v229
	v_mov_b32_e32 v233, 0
	v_mov_b32_e32 v242, 0
	s_barrier
	v_readlane_b32 s13, v253, 51
	s_waitcnt vmcnt(0)
	v_add_f32_e32 v134, v144, v145
	v_add_f32_e32 v135, v148, v149
	v_add_f32_e32 v134, v134, v135
	v_mov_b32_e32 v135, v134
	s_nop 1
	v_permlane16_swap_b32_e32 v134, v135
	v_add_f32_e32 v134, v134, v135
	v_mov_b32_e32 v135, v134
	s_nop 1
	v_permlane32_swap_b32_e32 v134, v135
	v_add_f32_e32 v134, v134, v135
	v_fmamk_f32 v134, v134, 0x3a800000, v236
	v_rsq_f32_e32 v140, v134
	v_add_f32_e32 v134, v150, v151
	v_add_f32_e32 v135, v152, v153
	v_add_f32_e32 v134, v134, v135
	v_mov_b32_e32 v135, v134
	s_nop 1
	v_permlane16_swap_b32_e32 v134, v135
	v_add_f32_e32 v134, v134, v135
	v_mov_b32_e32 v135, v134
	s_nop 1
	v_permlane32_swap_b32_e32 v134, v135
	v_add_f32_e32 v134, v134, v135
	v_fmamk_f32 v134, v134, 0x3a800000, v236
	v_rsq_f32_e32 v144, v134
	v_add_f32_e32 v134, v154, v155
	v_add_f32_e32 v135, v157, v158
	v_add_f32_e32 v134, v134, v135
	v_mov_b32_e32 v135, v134
	s_nop 1
	v_permlane16_swap_b32_e32 v134, v135
	v_add_f32_e32 v134, v134, v135
	v_mov_b32_e32 v135, v134
	s_nop 1
	v_permlane32_swap_b32_e32 v134, v135
	v_add_f32_e32 v134, v134, v135
	v_fmamk_f32 v134, v134, 0x3a800000, v236
	v_rsq_f32_e32 v148, v134
	v_add_f32_e32 v134, v159, v160
	v_add_f32_e32 v135, v161, v162
	v_add_f32_e32 v134, v134, v135
	v_mov_b32_e32 v135, v134
	s_nop 1
	v_permlane16_swap_b32_e32 v134, v135
	v_add_f32_e32 v134, v134, v135
	v_mov_b32_e32 v135, v134
	s_nop 1
	v_permlane32_swap_b32_e32 v134, v135
	v_add_f32_e32 v134, v134, v135
	v_fmamk_f32 v134, v134, 0x3a800000, v236
	v_rsq_f32_e32 v150, v134
	v_add_f32_e32 v134, v163, v164
	v_add_f32_e32 v135, v165, v166
	v_add_f32_e32 v134, v134, v135
	v_mov_b32_e32 v135, v134
	s_nop 1
	v_permlane16_swap_b32_e32 v134, v135
	v_add_f32_e32 v134, v134, v135
	v_mov_b32_e32 v135, v134
	s_nop 1
	v_permlane32_swap_b32_e32 v134, v135
	v_add_f32_e32 v134, v134, v135
	v_add_f32_e32 v135, v167, v168
	v_add_f32_e32 v137, v169, v170
	v_add_f32_e32 v135, v135, v137
	v_mov_b32_e32 v137, v135
	s_nop 1
	v_permlane16_swap_b32_e32 v135, v137
	v_add_f32_e32 v135, v135, v137
	v_mov_b32_e32 v137, v135
	s_nop 1
	v_permlane32_swap_b32_e32 v135, v137
	v_add_f32_e32 v135, v135, v137
	v_add_f32_e32 v137, v171, v172
	v_add_f32_e32 v138, v141, v138
	v_add_f32_e32 v137, v137, v138
	v_mov_b32_e32 v138, v137
	s_nop 1
	v_permlane16_swap_b32_e32 v137, v138
	v_add_f32_e32 v137, v137, v138
	v_mov_b32_e32 v138, v137
	s_nop 1
	v_permlane32_swap_b32_e32 v137, v138
	v_add_f32_e32 v137, v137, v138
	v_fmamk_f32 v137, v137, 0x3a800000, v236
	v_rsq_f32_e32 v152, v137
	v_add_f32_e32 v137, v139, v173
	v_add_f32_e32 v136, v174, v136
	v_add_f32_e32 v136, v137, v136
	v_mov_b32_e32 v137, v136
	s_nop 1
	v_permlane16_swap_b32_e32 v136, v137
	v_add_f32_e32 v136, v136, v137
	v_fmamk_f32 v134, v134, 0x3a800000, v236
	v_fmamk_f32 v135, v135, 0x3a800000, v236
	v_mov_b32_e32 v137, v136
	v_rsq_f32_e32 v134, v134
	v_rsq_f32_e32 v135, v135
	v_permlane32_swap_b32_e32 v136, v137
	v_add_f32_e32 v136, v136, v137
	v_fmamk_f32 v136, v136, 0x3a800000, v236
	v_rsq_f32_e32 v154, v136
	v_mov_b64_e32 v[138:139], v[136:137]
	v_mov_b64_e32 v[158:159], v[142:143]
	v_mov_b64_e32 v[136:137], v[134:135]
	v_mov_b32_e32 v229, v150
	v_mov_b32_e32 v230, v148
	v_mov_b32_e32 v231, v144
	v_mov_b32_e32 v232, v140
	v_mov_b32_e32 v2, v134
	v_mov_b32_e32 v3, v135
	v_mov_b32_e32 v233, v152
	v_mov_b32_e32 v242, v154
	s_mov_b32 s60, s58
	s_branch .LBB0_937
